# v83 + hot loop headers aligned to 256 bytes
# speedup vs baseline: 1.0040x; 1.0011x over previous
.LBB0_225:
	s_ashr_i32 s17, s16, 31
	s_lshl_b64 s[18:19], s[16:17], 20
	s_add_u32 s18, s30, s18
	s_addc_u32 s19, s31, s19
	s_and_b64 s[20:21], s[4:5], exec
	s_cselect_b32 s17, s19, s25
	s_cselect_b32 s54, s18, s24
	s_ashr_i32 s15, s14, 31
	s_lshl_b64 s[20:21], s[14:15], 20
	s_add_u32 s20, s34, s20
	s_addc_u32 s21, s35, s21
	s_and_b64 s[28:29], s[4:5], exec
	s_cselect_b32 s15, s21, s27
	s_cselect_b32 s55, s20, s26
	s_add_u32 s24, s24, 0x80080
	s_addc_u32 s25, s25, 0
	s_add_u32 s58, s26, 0x100
	v_mov_b32_e32 v0, 0
	s_addc_u32 s59, s27, 0
	s_mov_b32 s60, -2
	v_mov_b32_e32 v1, v0
	v_mov_b32_e32 v2, v0
	v_mov_b32_e32 v3, v0
	v_mov_b32_e32 v4, v0
	v_mov_b32_e32 v5, v0
	v_mov_b32_e32 v6, v0
	v_mov_b32_e32 v7, v0
	v_mov_b32_e32 v8, v0
	v_mov_b32_e32 v9, v0
	v_mov_b32_e32 v10, v0
	v_mov_b32_e32 v11, v0
	v_mov_b32_e32 v16, v0
	v_mov_b32_e32 v17, v0
	v_mov_b32_e32 v18, v0
	v_mov_b32_e32 v19, v0
	v_mov_b32_e32 v24, v0
	v_mov_b32_e32 v25, v0
	v_mov_b32_e32 v26, v0
	v_mov_b32_e32 v27, v0
	v_mov_b32_e32 v32, v0
	v_mov_b32_e32 v33, v0
	v_mov_b32_e32 v34, v0
	v_mov_b32_e32 v35, v0
	v_mov_b32_e32 v40, v0
	v_mov_b32_e32 v41, v0
	v_mov_b32_e32 v42, v0
	v_mov_b32_e32 v43, v0
	v_mov_b32_e32 v48, v0
	v_mov_b32_e32 v49, v0
	v_mov_b32_e32 v50, v0
	v_mov_b32_e32 v51, v0
	v_mov_b32_e32 v12, v0
	v_mov_b32_e32 v13, v0
	v_mov_b32_e32 v14, v0
	v_mov_b32_e32 v15, v0
	v_mov_b32_e32 v20, v0
	v_mov_b32_e32 v21, v0
	v_mov_b32_e32 v22, v0
	v_mov_b32_e32 v23, v0
	v_mov_b32_e32 v28, v0
	v_mov_b32_e32 v29, v0
	v_mov_b32_e32 v30, v0
	v_mov_b32_e32 v31, v0
	v_mov_b32_e32 v36, v0
	v_mov_b32_e32 v37, v0
	v_mov_b32_e32 v38, v0
	v_mov_b32_e32 v39, v0
	v_mov_b32_e32 v44, v0
	v_mov_b32_e32 v45, v0
	v_mov_b32_e32 v46, v0
	v_mov_b32_e32 v47, v0
	v_mov_b32_e32 v52, v0
	v_mov_b32_e32 v53, v0
	v_mov_b32_e32 v54, v0
	v_mov_b32_e32 v55, v0
	v_mov_b32_e32 v56, v0
	v_mov_b32_e32 v57, v0
	v_mov_b32_e32 v58, v0
	v_mov_b32_e32 v59, v0
	v_mov_b32_e32 v60, v0
	v_mov_b32_e32 v61, v0
	v_mov_b32_e32 v62, v0
	v_mov_b32_e32 v63, v0
	v_mov_b32_e32 v64, v0
	v_mov_b32_e32 v65, v0
	v_mov_b32_e32 v66, v0
	v_mov_b32_e32 v67, v0
	v_mov_b32_e32 v68, v0
	v_mov_b32_e32 v69, v0
	v_mov_b32_e32 v70, v0
	v_mov_b32_e32 v71, v0
	v_mov_b32_e32 v72, v0
	v_mov_b32_e32 v73, v0
	v_mov_b32_e32 v74, v0
	v_mov_b32_e32 v75, v0
	v_mov_b32_e32 v80, v0
	v_mov_b32_e32 v81, v0
	v_mov_b32_e32 v82, v0
	v_mov_b32_e32 v83, v0
	v_mov_b32_e32 v88, v0
	v_mov_b32_e32 v89, v0
	v_mov_b32_e32 v90, v0
	v_mov_b32_e32 v91, v0
	v_mov_b32_e32 v96, v0
	v_mov_b32_e32 v97, v0
	v_mov_b32_e32 v98, v0
	v_mov_b32_e32 v99, v0
	v_mov_b32_e32 v104, v0
	v_mov_b32_e32 v105, v0
	v_mov_b32_e32 v106, v0
	v_mov_b32_e32 v107, v0
	v_mov_b32_e32 v112, v0
	v_mov_b32_e32 v113, v0
	v_mov_b32_e32 v114, v0
	v_mov_b32_e32 v115, v0
	v_mov_b32_e32 v76, v0
	v_mov_b32_e32 v77, v0
	v_mov_b32_e32 v78, v0
	v_mov_b32_e32 v79, v0
	v_mov_b32_e32 v84, v0
	v_mov_b32_e32 v85, v0
	v_mov_b32_e32 v86, v0
	v_mov_b32_e32 v87, v0
	v_mov_b32_e32 v92, v0
	v_mov_b32_e32 v93, v0
	v_mov_b32_e32 v94, v0
	v_mov_b32_e32 v95, v0
	v_mov_b32_e32 v100, v0
	v_mov_b32_e32 v101, v0
	v_mov_b32_e32 v102, v0
	v_mov_b32_e32 v103, v0
	v_mov_b32_e32 v108, v0
	v_mov_b32_e32 v109, v0
	v_mov_b32_e32 v110, v0
	v_mov_b32_e32 v111, v0
	v_mov_b32_e32 v116, v0
	v_mov_b32_e32 v117, v0
	v_mov_b32_e32 v118, v0
	v_mov_b32_e32 v119, v0
	v_mov_b32_e32 v120, v0
	v_mov_b32_e32 v121, v0
	v_mov_b32_e32 v122, v0
	v_mov_b32_e32 v123, v0
	v_mov_b32_e32 v124, v0
	v_mov_b32_e32 v125, v0
	v_mov_b32_e32 v126, v0
	v_mov_b32_e32 v127, v0
	.p2alignl 8, 3212836864

.LBB0_455:
	s_lshl_b32 s54, s73, 1
	s_and_b32 s95, s54, 0xc00
	s_and_b32 s54, s75, -16
	s_lshl_b32 s33, s90, 22
	s_ashr_i32 s55, s54, 31
	s_and_b32 s18, s90, 7
	s_and_b32 s33, s33, 0x1000000
	s_lshl_b64 s[60:61], s[54:55], 1
	s_add_u32 s54, s60, s95
	s_addc_u32 s55, s61, 0
	s_add_u32 s54, s54, s33
	s_addc_u32 s55, s55, 0
	s_and_b32 s93, s91, 7
	v_lshl_add_u64 v[164:165], s[54:55], 0, v[150:151]
	s_lshl_b32 s62, s18, 21
	s_mov_b32 s63, s19
	s_lshl_b32 s64, s18, 16
	s_mov_b32 s65, s19
	s_lshl_b32 s92, s93, 6
	s_lshl_b32 s94, s93, 20
	s_mov_b64 s[66:67], -1
	s_and_b64 vcc, exec, s[16:17]
	s_cbranch_vccz .LBB0_459
	s_mov_b64 s[54:55], s[0:1]
	s_load_dwordx2 s[66:67], s[54:55], 0x80
	s_lshl_b32 s18, s18, 19
	v_lshl_add_u64 v[170:171], v[156:157], 0, s[18:19]
	s_lshl_b32 s18, s94, 1
	v_mov_b32_e32 v132, 0
	s_waitcnt lgkmcnt(0)
	s_add_u32 s18, s66, s18
	s_addc_u32 s33, s67, 0
	s_add_u32 s54, s18, s20
	s_addc_u32 s55, s33, s21
	s_lshl_b32 s18, s92, 13
	s_add_u32 s18, s66, s18
	s_addc_u32 s33, s67, 0
	s_add_u32 s96, s18, s24
	s_addc_u32 s97, s33, s25
	s_lshl_b32 s18, s92, 10
	s_add_u32 s18, s66, s18
	s_addc_u32 s33, s67, 0
	s_add_u32 s56, s18, s22
	v_lshl_add_u64 v[24:25], s[96:97], 0, v[140:141]
	s_mov_b32 s18, 0x15700000
	v_add_co_u32_e32 v0, vcc, s18, v24
	v_lshl_add_u64 v[26:27], s[54:55], 0, v[140:141]
	s_nop 0
	v_addc_co_u32_e32 v1, vcc, 0, v25, vcc
	v_add_co_u32_e32 v4, vcc, s78, v26
	s_addc_u32 s57, s33, s23
	s_nop 0
	v_addc_co_u32_e32 v5, vcc, 0, v27, vcc
	global_load_dwordx4 v[0:3], v[0:1], off
	v_lshl_add_u64 v[174:175], v[26:27], 0, s[30:31]
	global_load_dwordx4 v[44:47], v[4:5], off
	global_load_dwordx4 v[52:55], v[174:175], off offset:1024
	global_load_dwordx4 v[28:31], v[174:175], off offset:2048
	global_load_dwordx4 v[20:23], v[174:175], off offset:3072
	v_add_co_u32_e32 v4, vcc, s79, v26
	s_waitcnt vmcnt(9)
	v_lshl_add_u64 v[32:33], s[56:57], 0, v[144:145]
	v_addc_co_u32_e32 v5, vcc, 0, v27, vcc
	v_lshl_add_u64 v[178:179], v[32:33], 0, s[36:37]
	v_add_co_u32_e32 v32, vcc, s80, v32
	s_mov_b64 s[96:97], 0x15700000
	s_nop 0
	v_addc_co_u32_e32 v33, vcc, 0, v33, vcc
	s_mov_b32 s18, 0x15702000
	v_lshl_add_u64 v[172:173], v[24:25], 0, s[96:97]
	v_add_co_u32_e32 v24, vcc, s18, v24
	v_lshl_add_u64 v[176:177], v[26:27], 0, s[34:35]
	s_nop 0
	v_addc_co_u32_e32 v25, vcc, 0, v25, vcc
	global_load_dwordx4 v[16:19], v[4:5], off
	global_load_dwordx4 v[12:15], v[176:177], off offset:1024
	s_nop 0
	global_load_dwordx4 v[4:7], v[176:177], off offset:2048
	global_load_dwordx4 v[8:11], v[176:177], off offset:3072
	global_load_dwordx4 v[40:43], v[32:33], off
	global_load_dwordx4 v[36:39], v[178:179], off offset:64
	v_add_co_u32_e32 v32, vcc, s81, v26
	global_load_dwordx4 v[60:63], v[24:25], off
	v_lshl_add_u64 v[24:25], v[26:27], 0, s[38:39]
	v_addc_co_u32_e32 v33, vcc, 0, v27, vcc
	global_load_dwordx4 v[72:75], v[32:33], off
	global_load_dwordx4 v[76:79], v[24:25], off offset:1024
	global_load_dwordx4 v[80:83], v[24:25], off offset:2048
	global_load_dwordx4 v[84:87], v[24:25], off offset:3072
	v_add_co_u32_e32 v24, vcc, 0x16708000, v26
	v_lshl_add_u64 v[32:33], v[26:27], 0, s[40:41]
	s_nop 0
	v_addc_co_u32_e32 v25, vcc, 0, v27, vcc
	global_load_dwordx4 v[56:59], v[24:25], off
	global_load_dwordx4 v[48:51], v[32:33], off offset:1024
	s_nop 0
	global_load_dwordx4 v[24:27], v[32:33], off offset:2048
	s_nop 0
	global_load_dwordx4 v[32:35], v[32:33], off offset:3072
	s_nop 0
	global_load_dwordx4 v[64:67], v[178:179], off offset:1024
	global_load_dwordx4 v[68:71], v[178:179], off offset:1088
	v_lshl_add_u64 v[166:167], v[152:153], 0, s[62:63]
	v_lshl_add_u64 v[168:169], v[154:155], 0, s[64:65]
	s_mov_b32 s18, -3
	v_mov_b64_e32 v[180:181], v[164:165]
	v_mov_b32_e32 v133, v132
	v_mov_b32_e32 v134, v132
	v_mov_b32_e32 v135, v132
	v_mov_b32_e32 v136, v132
	v_mov_b32_e32 v137, v132
	v_mov_b32_e32 v138, v132
	v_mov_b32_e32 v139, v132
	s_barrier
	.p2alignl 8, 3212836864

.LBB0_459:
	s_and_b64 vcc, exec, s[66:67]
	s_cbranch_vccz .LBB0_454
	s_lshl_b32 s18, s90, 10
	s_and_b32 s18, s18, 0x1000
	v_add_u32_e32 v0, s18, v199
	v_mad_u64_u32 v[0:1], s[54:55], v0, s89, 0
	s_add_u32 s54, s60, s95
	v_or_b32_e32 v0, v162, v0
	s_addc_u32 s55, s61, 0
	v_lshl_add_u64 v[170:171], s[54:55], 0, v[0:1]
	s_mov_b64 s[54:55], s[0:1]
	s_load_dwordx2 s[60:61], s[54:55], 0x80
	s_lshl_b32 s18, s94, 1
	v_lshl_add_u64 v[168:169], v[160:161], 0, s[64:65]
	v_lshl_add_u64 v[166:167], v[158:159], 0, s[62:63]
	s_mov_b64 s[66:67], 0xe601000
	s_waitcnt lgkmcnt(0)
	s_add_u32 s18, s60, s18
	s_addc_u32 s33, s61, 0
	s_add_u32 s54, s18, s26
	s_addc_u32 s55, s33, s27
	s_lshl_b32 s18, s93, 10
	s_and_b32 s64, s18, 0x1000
	s_lshl_b32 s18, s91, 9
	v_add_u32_e32 v2, s64, v198
	v_mov_b64_e32 v[0:1], s[60:61]
	s_and_b32 s65, s18, 0x600
	v_mad_u64_u32 v[0:1], s[62:63], v2, s89, v[0:1]
	s_lshl_b32 s18, s65, 1
	v_lshl_add_u64 v[0:1], v[0:1], 0, s[18:19]
	s_lshl_b32 s18, s91, 1
	s_and_b32 s62, s18, -16
	s_ashr_i32 s63, s62, 31
	s_lshl_b32 s18, s92, 10
	v_lshl_add_u64 v[0:1], s[62:63], 1, v[0:1]
	s_add_u32 s18, s60, s18
	s_waitcnt vmcnt(8)
	v_lshl_add_u64 v[36:37], v[0:1], 0, v[142:143]
	s_addc_u32 s33, s61, 0
	v_lshl_add_u64 v[172:173], v[36:37], 0, s[66:67]
	s_add_u32 s66, s18, s28
	s_mov_b32 s18, 0xe601000
	v_add_co_u32_e32 v0, vcc, s18, v36
	s_waitcnt vmcnt(7)
	v_lshl_add_u64 v[44:45], s[54:55], 0, v[140:141]
	v_addc_co_u32_e32 v1, vcc, 0, v37, vcc
	global_load_dwordx4 v[84:87], v[0:1], off
	v_add_co_u32_e32 v0, vcc, s78, v44
	s_addc_u32 s67, s33, s29
	s_nop 0
	v_addc_co_u32_e32 v1, vcc, 0, v45, vcc
	v_add_co_u32_e32 v16, vcc, s79, v44
	s_waitcnt vmcnt(5)
	v_lshl_add_u64 v[32:33], s[66:67], 0, v[144:145]
	v_addc_co_u32_e32 v17, vcc, 0, v45, vcc
	v_lshl_add_u64 v[178:179], v[32:33], 0, s[36:37]
	v_add_co_u32_e32 v32, vcc, s80, v32
	s_mov_b32 s18, 0xe6c1000
	s_nop 0
	v_addc_co_u32_e32 v33, vcc, 0, v33, vcc
	v_add_co_u32_e32 v36, vcc, s18, v36
	s_mov_b32 s18, 0x16708000
	s_nop 0
	v_addc_co_u32_e32 v37, vcc, 0, v37, vcc
	v_add_co_u32_e32 v38, vcc, s81, v44
	v_lshl_add_u64 v[174:175], v[44:45], 0, s[30:31]
	s_nop 0
	v_addc_co_u32_e32 v39, vcc, 0, v45, vcc
	global_load_dwordx4 v[12:15], v[0:1], off
	global_load_dwordx4 v[8:11], v[174:175], off offset:1024
	global_load_dwordx4 v[4:7], v[174:175], off offset:2048
	s_nop 0
	global_load_dwordx4 v[0:3], v[174:175], off offset:3072
	v_lshl_add_u64 v[176:177], v[44:45], 0, s[34:35]
	global_load_dwordx4 v[24:27], v[16:17], off
	global_load_dwordx4 v[28:31], v[176:177], off offset:1024
	global_load_dwordx4 v[20:23], v[176:177], off offset:2048
	s_nop 0
	global_load_dwordx4 v[16:19], v[176:177], off offset:3072
	global_load_dwordx4 v[40:43], v[32:33], off
	s_nop 0
	global_load_dwordx4 v[32:35], v[178:179], off offset:64
	global_load_dwordx4 v[80:83], v[36:37], off
	v_lshl_add_u64 v[36:37], v[44:45], 0, s[38:39]
	v_lshl_add_u64 v[52:53], v[44:45], 0, s[40:41]
	v_add_co_u32_e32 v44, vcc, s18, v44
	global_load_dwordx4 v[64:67], v[38:39], off
	global_load_dwordx4 v[68:71], v[36:37], off offset:1024
	global_load_dwordx4 v[56:59], v[36:37], off offset:2048
	s_nop 0
	global_load_dwordx4 v[36:39], v[36:37], off offset:3072
	v_addc_co_u32_e32 v45, vcc, 0, v45, vcc
	global_load_dwordx4 v[44:47], v[44:45], off
	s_nop 0
	global_load_dwordx4 v[60:63], v[52:53], off offset:1024
	global_load_dwordx4 v[48:51], v[52:53], off offset:2048
	s_nop 0
	global_load_dwordx4 v[52:55], v[52:53], off offset:3072
	s_nop 0
	global_load_dwordx4 v[76:79], v[178:179], off offset:1024
	global_load_dwordx4 v[72:75], v[178:179], off offset:1088
	v_mov_b32_e32 v128, 0
	v_add_u32_e32 v88, s70, v140
	s_mov_b32 s18, -3
	s_movk_i32 s66, 0x800
	v_mov_b32_e32 v129, v128
	v_mov_b32_e32 v130, v128
	v_mov_b32_e32 v131, v128
	v_mov_b32_e32 v132, v128
	v_mov_b32_e32 v133, v128
	v_mov_b32_e32 v134, v128
	v_mov_b32_e32 v135, v128
	s_waitcnt vmcnt(21)
	ds_write_b128 v88, v[84:87]
	s_waitcnt lgkmcnt(0)
	s_barrier
	.p2alignl 8, 3212836864

.LBB0_588:
	s_ashr_i32 s35, s34, 31
	s_lshl_b64 s[36:37], s[34:35], 20
	s_add_u32 s36, s60, s36
	s_addc_u32 s37, s61, s37
	s_and_b64 s[38:39], s[8:9], exec
	s_cselect_b32 s35, s37, s49
	s_cselect_b32 s41, s36, s48
	s_ashr_i32 s31, s30, 31
	s_lshl_b64 s[38:39], s[30:31], 20
	s_add_u32 s38, s62, s38
	s_addc_u32 s39, s63, s39
	s_and_b64 s[54:55], s[8:9], exec
	s_cselect_b32 s31, s39, s51
	s_cselect_b32 s73, s38, s50
	s_add_u32 s48, s48, 0x80080
	s_addc_u32 s49, s49, 0
	s_add_u32 s74, s50, 0x100
	v_mov_b32_e32 v0, 0
	s_addc_u32 s75, s51, 0
	s_mov_b32 s77, -2
	s_waitcnt lgkmcnt(0)
	v_mov_b32_e32 v1, v0
	v_mov_b32_e32 v2, v0
	v_mov_b32_e32 v3, v0
	v_mov_b32_e32 v4, v0
	v_mov_b32_e32 v5, v0
	v_mov_b32_e32 v6, v0
	v_mov_b32_e32 v7, v0
	v_mov_b32_e32 v16, v0
	v_mov_b32_e32 v17, v0
	v_mov_b32_e32 v18, v0
	v_mov_b32_e32 v19, v0
	v_mov_b32_e32 v20, v0
	v_mov_b32_e32 v21, v0
	v_mov_b32_e32 v22, v0
	v_mov_b32_e32 v23, v0
	v_mov_b32_e32 v32, v0
	v_mov_b32_e32 v33, v0
	v_mov_b32_e32 v34, v0
	v_mov_b32_e32 v35, v0
	v_mov_b32_e32 v36, v0
	v_mov_b32_e32 v37, v0
	v_mov_b32_e32 v38, v0
	v_mov_b32_e32 v39, v0
	v_mov_b32_e32 v48, v0
	v_mov_b32_e32 v49, v0
	v_mov_b32_e32 v50, v0
	v_mov_b32_e32 v51, v0
	v_mov_b32_e32 v52, v0
	v_mov_b32_e32 v53, v0
	v_mov_b32_e32 v54, v0
	v_mov_b32_e32 v55, v0
	v_mov_b32_e32 v8, v0
	v_mov_b32_e32 v9, v0
	v_mov_b32_e32 v10, v0
	v_mov_b32_e32 v11, v0
	v_mov_b32_e32 v12, v0
	v_mov_b32_e32 v13, v0
	v_mov_b32_e32 v14, v0
	v_mov_b32_e32 v15, v0
	v_mov_b32_e32 v24, v0
	v_mov_b32_e32 v25, v0
	v_mov_b32_e32 v26, v0
	v_mov_b32_e32 v27, v0
	v_mov_b32_e32 v28, v0
	v_mov_b32_e32 v29, v0
	v_mov_b32_e32 v30, v0
	v_mov_b32_e32 v31, v0
	v_mov_b32_e32 v40, v0
	v_mov_b32_e32 v41, v0
	v_mov_b32_e32 v42, v0
	v_mov_b32_e32 v43, v0
	v_mov_b32_e32 v44, v0
	v_mov_b32_e32 v45, v0
	v_mov_b32_e32 v46, v0
	v_mov_b32_e32 v47, v0
	v_mov_b32_e32 v56, v0
	v_mov_b32_e32 v57, v0
	v_mov_b32_e32 v58, v0
	v_mov_b32_e32 v59, v0
	v_mov_b32_e32 v60, v0
	v_mov_b32_e32 v61, v0
	v_mov_b32_e32 v62, v0
	v_mov_b32_e32 v63, v0
	v_mov_b32_e32 v64, v0
	v_mov_b32_e32 v65, v0
	v_mov_b32_e32 v66, v0
	v_mov_b32_e32 v67, v0
	v_mov_b32_e32 v68, v0
	v_mov_b32_e32 v69, v0
	v_mov_b32_e32 v70, v0
	v_mov_b32_e32 v71, v0
	v_mov_b32_e32 v80, v0
	v_mov_b32_e32 v81, v0
	v_mov_b32_e32 v82, v0
	v_mov_b32_e32 v83, v0
	v_mov_b32_e32 v84, v0
	v_mov_b32_e32 v85, v0
	v_mov_b32_e32 v86, v0
	v_mov_b32_e32 v87, v0
	v_mov_b32_e32 v96, v0
	v_mov_b32_e32 v97, v0
	v_mov_b32_e32 v98, v0
	v_mov_b32_e32 v99, v0
	v_mov_b32_e32 v100, v0
	v_mov_b32_e32 v101, v0
	v_mov_b32_e32 v102, v0
	v_mov_b32_e32 v103, v0
	v_mov_b32_e32 v112, v0
	v_mov_b32_e32 v113, v0
	v_mov_b32_e32 v114, v0
	v_mov_b32_e32 v115, v0
	v_mov_b32_e32 v116, v0
	v_mov_b32_e32 v117, v0
	v_mov_b32_e32 v118, v0
	v_mov_b32_e32 v119, v0
	v_mov_b32_e32 v72, v0
	v_mov_b32_e32 v73, v0
	v_mov_b32_e32 v74, v0
	v_mov_b32_e32 v75, v0
	v_mov_b32_e32 v76, v0
	v_mov_b32_e32 v77, v0
	v_mov_b32_e32 v78, v0
	v_mov_b32_e32 v79, v0
	v_mov_b32_e32 v88, v0
	v_mov_b32_e32 v89, v0
	v_mov_b32_e32 v90, v0
	v_mov_b32_e32 v91, v0
	v_mov_b32_e32 v92, v0
	v_mov_b32_e32 v93, v0
	v_mov_b32_e32 v94, v0
	v_mov_b32_e32 v95, v0
	v_mov_b32_e32 v104, v0
	v_mov_b32_e32 v105, v0
	v_mov_b32_e32 v106, v0
	v_mov_b32_e32 v107, v0
	v_mov_b32_e32 v108, v0
	v_mov_b32_e32 v109, v0
	v_mov_b32_e32 v110, v0
	v_mov_b32_e32 v111, v0
	v_mov_b32_e32 v120, v0
	v_mov_b32_e32 v121, v0
	v_mov_b32_e32 v122, v0
	v_mov_b32_e32 v123, v0
	v_mov_b32_e32 v124, v0
	v_mov_b32_e32 v125, v0
	v_mov_b32_e32 v126, v0
	v_mov_b32_e32 v127, v0
	.p2alignl 8, 3212836864

.LBB0_672:
	s_ashr_i32 s25, s24, 31
	s_lshl_b64 s[26:27], s[24:25], 20
	s_add_u32 s26, s38, s26
	s_addc_u32 s27, s39, s27
	s_and_b64 s[28:29], s[6:7], exec
	s_cselect_b32 s25, s27, s31
	s_cselect_b32 s65, s26, s30
	s_ashr_i32 s23, s22, 31
	s_lshl_b64 s[28:29], s[22:23], 20
	s_add_u32 s28, s40, s28
	s_addc_u32 s29, s41, s29
	s_and_b64 s[36:37], s[6:7], exec
	s_cselect_b32 s23, s29, s35
	s_cselect_b32 s66, s28, s34
	s_add_u32 s30, s30, 0x80080
	s_addc_u32 s31, s31, 0
	s_add_u32 s67, s34, 0x100
	v_mov_b32_e32 v8, 0
	s_addc_u32 s68, s35, 0
	s_mov_b32 s69, -2
	v_mov_b32_e32 v9, v8
	v_mov_b32_e32 v10, v8
	v_mov_b32_e32 v11, v8
	v_mov_b32_e32 v12, v8
	v_mov_b32_e32 v13, v8
	v_mov_b32_e32 v14, v8
	v_mov_b32_e32 v15, v8
	v_mov_b32_e32 v24, v8
	v_mov_b32_e32 v25, v8
	v_mov_b32_e32 v26, v8
	v_mov_b32_e32 v27, v8
	v_mov_b32_e32 v28, v8
	v_mov_b32_e32 v29, v8
	v_mov_b32_e32 v30, v8
	v_mov_b32_e32 v31, v8
	v_mov_b32_e32 v40, v8
	v_mov_b32_e32 v41, v8
	v_mov_b32_e32 v42, v8
	v_mov_b32_e32 v43, v8
	v_mov_b32_e32 v44, v8
	v_mov_b32_e32 v45, v8
	v_mov_b32_e32 v46, v8
	v_mov_b32_e32 v47, v8
	v_mov_b32_e32 v56, v8
	v_mov_b32_e32 v57, v8
	v_mov_b32_e32 v58, v8
	v_mov_b32_e32 v59, v8
	v_mov_b32_e32 v60, v8
	v_mov_b32_e32 v61, v8
	v_mov_b32_e32 v62, v8
	v_mov_b32_e32 v63, v8
	v_mov_b32_e32 v0, v8
	v_mov_b32_e32 v1, v8
	v_mov_b32_e32 v2, v8
	v_mov_b32_e32 v3, v8
	v_mov_b32_e32 v4, v8
	v_mov_b32_e32 v5, v8
	v_mov_b32_e32 v6, v8
	v_mov_b32_e32 v7, v8
	v_mov_b32_e32 v16, v8
	v_mov_b32_e32 v17, v8
	v_mov_b32_e32 v18, v8
	v_mov_b32_e32 v19, v8
	v_mov_b32_e32 v20, v8
	v_mov_b32_e32 v21, v8
	v_mov_b32_e32 v22, v8
	v_mov_b32_e32 v23, v8
	v_mov_b32_e32 v32, v8
	v_mov_b32_e32 v33, v8
	v_mov_b32_e32 v34, v8
	v_mov_b32_e32 v35, v8
	v_mov_b32_e32 v36, v8
	v_mov_b32_e32 v37, v8
	v_mov_b32_e32 v38, v8
	v_mov_b32_e32 v39, v8
	v_mov_b32_e32 v48, v8
	v_mov_b32_e32 v49, v8
	v_mov_b32_e32 v50, v8
	v_mov_b32_e32 v51, v8
	v_mov_b32_e32 v52, v8
	v_mov_b32_e32 v53, v8
	v_mov_b32_e32 v54, v8
	v_mov_b32_e32 v55, v8
	v_mov_b32_e32 v72, v8
	v_mov_b32_e32 v73, v8
	v_mov_b32_e32 v74, v8
	v_mov_b32_e32 v75, v8
	v_mov_b32_e32 v76, v8
	v_mov_b32_e32 v77, v8
	v_mov_b32_e32 v78, v8
	v_mov_b32_e32 v79, v8
	v_mov_b32_e32 v88, v8
	v_mov_b32_e32 v89, v8
	v_mov_b32_e32 v90, v8
	v_mov_b32_e32 v91, v8
	v_mov_b32_e32 v92, v8
	v_mov_b32_e32 v93, v8
	v_mov_b32_e32 v94, v8
	v_mov_b32_e32 v95, v8
	v_mov_b32_e32 v104, v8
	v_mov_b32_e32 v105, v8
	v_mov_b32_e32 v106, v8
	v_mov_b32_e32 v107, v8
	v_mov_b32_e32 v108, v8
	v_mov_b32_e32 v109, v8
	v_mov_b32_e32 v110, v8
	v_mov_b32_e32 v111, v8
	v_mov_b32_e32 v120, v8
	v_mov_b32_e32 v121, v8
	v_mov_b32_e32 v122, v8
	v_mov_b32_e32 v123, v8
	v_mov_b32_e32 v124, v8
	v_mov_b32_e32 v125, v8
	v_mov_b32_e32 v126, v8
	v_mov_b32_e32 v127, v8
	v_mov_b32_e32 v64, v8
	v_mov_b32_e32 v65, v8
	v_mov_b32_e32 v66, v8
	v_mov_b32_e32 v67, v8
	v_mov_b32_e32 v68, v8
	v_mov_b32_e32 v69, v8
	v_mov_b32_e32 v70, v8
	v_mov_b32_e32 v71, v8
	v_mov_b32_e32 v80, v8
	v_mov_b32_e32 v81, v8
	v_mov_b32_e32 v82, v8
	v_mov_b32_e32 v83, v8
	v_mov_b32_e32 v84, v8
	v_mov_b32_e32 v85, v8
	v_mov_b32_e32 v86, v8
	v_mov_b32_e32 v87, v8
	v_mov_b32_e32 v96, v8
	v_mov_b32_e32 v97, v8
	v_mov_b32_e32 v98, v8
	v_mov_b32_e32 v99, v8
	v_mov_b32_e32 v100, v8
	v_mov_b32_e32 v101, v8
	v_mov_b32_e32 v102, v8
	v_mov_b32_e32 v103, v8
	v_mov_b32_e32 v112, v8
	v_mov_b32_e32 v113, v8
	v_mov_b32_e32 v114, v8
	v_mov_b32_e32 v115, v8
	v_mov_b32_e32 v116, v8
	v_mov_b32_e32 v117, v8
	v_mov_b32_e32 v118, v8
	v_mov_b32_e32 v119, v8
	.p2alignl 8, 3212836864

.LBB0_1186:
	s_add_u32 s66, s30, 0x100
	v_mov_b32_e32 v0, 0
	s_addc_u32 s67, s31, 0
	s_mov_b32 s68, -2
	s_waitcnt lgkmcnt(0)
	v_mov_b32_e32 v1, v0
	v_mov_b32_e32 v2, v0
	v_mov_b32_e32 v3, v0
	v_mov_b32_e32 v4, v0
	v_mov_b32_e32 v5, v0
	v_mov_b32_e32 v6, v0
	v_mov_b32_e32 v7, v0
	v_mov_b32_e32 v16, v0
	v_mov_b32_e32 v17, v0
	v_mov_b32_e32 v18, v0
	v_mov_b32_e32 v19, v0
	v_mov_b32_e32 v20, v0
	v_mov_b32_e32 v21, v0
	v_mov_b32_e32 v22, v0
	v_mov_b32_e32 v23, v0
	v_mov_b32_e32 v32, v0
	v_mov_b32_e32 v33, v0
	v_mov_b32_e32 v34, v0
	v_mov_b32_e32 v35, v0
	v_mov_b32_e32 v36, v0
	v_mov_b32_e32 v37, v0
	v_mov_b32_e32 v38, v0
	v_mov_b32_e32 v39, v0
	v_mov_b32_e32 v48, v0
	v_mov_b32_e32 v49, v0
	v_mov_b32_e32 v50, v0
	v_mov_b32_e32 v51, v0
	v_mov_b32_e32 v52, v0
	v_mov_b32_e32 v53, v0
	v_mov_b32_e32 v54, v0
	v_mov_b32_e32 v55, v0
	v_mov_b32_e32 v8, v0
	v_mov_b32_e32 v9, v0
	v_mov_b32_e32 v10, v0
	v_mov_b32_e32 v11, v0
	v_mov_b32_e32 v12, v0
	v_mov_b32_e32 v13, v0
	v_mov_b32_e32 v14, v0
	v_mov_b32_e32 v15, v0
	v_mov_b32_e32 v24, v0
	v_mov_b32_e32 v25, v0
	v_mov_b32_e32 v26, v0
	v_mov_b32_e32 v27, v0
	v_mov_b32_e32 v28, v0
	v_mov_b32_e32 v29, v0
	v_mov_b32_e32 v30, v0
	v_mov_b32_e32 v31, v0
	v_mov_b32_e32 v40, v0
	v_mov_b32_e32 v41, v0
	v_mov_b32_e32 v42, v0
	v_mov_b32_e32 v43, v0
	v_mov_b32_e32 v44, v0
	v_mov_b32_e32 v45, v0
	v_mov_b32_e32 v46, v0
	v_mov_b32_e32 v47, v0
	v_mov_b32_e32 v56, v0
	v_mov_b32_e32 v57, v0
	v_mov_b32_e32 v58, v0
	v_mov_b32_e32 v59, v0
	v_mov_b32_e32 v60, v0
	v_mov_b32_e32 v61, v0
	v_mov_b32_e32 v62, v0
	v_mov_b32_e32 v63, v0
	v_mov_b32_e32 v64, v0
	v_mov_b32_e32 v65, v0
	v_mov_b32_e32 v66, v0
	v_mov_b32_e32 v67, v0
	v_mov_b32_e32 v68, v0
	v_mov_b32_e32 v69, v0
	v_mov_b32_e32 v70, v0
	v_mov_b32_e32 v71, v0
	v_mov_b32_e32 v80, v0
	v_mov_b32_e32 v81, v0
	v_mov_b32_e32 v82, v0
	v_mov_b32_e32 v83, v0
	v_mov_b32_e32 v84, v0
	v_mov_b32_e32 v85, v0
	v_mov_b32_e32 v86, v0
	v_mov_b32_e32 v87, v0
	v_mov_b32_e32 v96, v0
	v_mov_b32_e32 v97, v0
	v_mov_b32_e32 v98, v0
	v_mov_b32_e32 v99, v0
	v_mov_b32_e32 v100, v0
	v_mov_b32_e32 v101, v0
	v_mov_b32_e32 v102, v0
	v_mov_b32_e32 v103, v0
	v_mov_b32_e32 v112, v0
	v_mov_b32_e32 v113, v0
	v_mov_b32_e32 v114, v0
	v_mov_b32_e32 v115, v0
	v_mov_b32_e32 v116, v0
	v_mov_b32_e32 v117, v0
	v_mov_b32_e32 v118, v0
	v_mov_b32_e32 v119, v0
	v_mov_b32_e32 v72, v0
	v_mov_b32_e32 v73, v0
	v_mov_b32_e32 v74, v0
	v_mov_b32_e32 v75, v0
	v_mov_b32_e32 v76, v0
	v_mov_b32_e32 v77, v0
	v_mov_b32_e32 v78, v0
	v_mov_b32_e32 v79, v0
	v_mov_b32_e32 v88, v0
	v_mov_b32_e32 v89, v0
	v_mov_b32_e32 v90, v0
	v_mov_b32_e32 v91, v0
	v_mov_b32_e32 v92, v0
	v_mov_b32_e32 v93, v0
	v_mov_b32_e32 v94, v0
	v_mov_b32_e32 v95, v0
	v_mov_b32_e32 v104, v0
	v_mov_b32_e32 v105, v0
	v_mov_b32_e32 v106, v0
	v_mov_b32_e32 v107, v0
	v_mov_b32_e32 v108, v0
	v_mov_b32_e32 v109, v0
	v_mov_b32_e32 v110, v0
	v_mov_b32_e32 v111, v0
	v_mov_b32_e32 v120, v0
	v_mov_b32_e32 v121, v0
	v_mov_b32_e32 v122, v0
	v_mov_b32_e32 v123, v0
	v_mov_b32_e32 v124, v0
	v_mov_b32_e32 v125, v0
	v_mov_b32_e32 v126, v0
	v_mov_b32_e32 v127, v0
	.p2alignl 8, 3212836864

.LBB0_1270:
	s_ashr_i32 s25, s24, 31
	s_lshl_b64 s[26:27], s[24:25], 20
	s_add_u32 s26, s38, s26
	s_addc_u32 s27, s39, s27
	s_and_b64 s[28:29], s[6:7], exec
	s_cselect_b32 s25, s27, s31
	s_cselect_b32 s63, s26, s30
	s_ashr_i32 s23, s22, 31
	s_lshl_b64 s[28:29], s[22:23], 20
	s_add_u32 s28, s40, s28
	s_addc_u32 s29, s41, s29
	s_and_b64 s[36:37], s[6:7], exec
	s_cselect_b32 s23, s29, s35
	s_cselect_b32 s64, s28, s34
	s_add_u32 s30, s30, 0x80080
	s_addc_u32 s31, s31, 0
	s_add_u32 s65, s34, 0x100
	v_mov_b32_e32 v0, 0
	s_addc_u32 s66, s35, 0
	s_mov_b32 s67, -2
	v_mov_b32_e32 v1, v0
	v_mov_b32_e32 v2, v0
	v_mov_b32_e32 v3, v0
	v_mov_b32_e32 v4, v0
	v_mov_b32_e32 v5, v0
	v_mov_b32_e32 v6, v0
	v_mov_b32_e32 v7, v0
	v_mov_b32_e32 v16, v0
	v_mov_b32_e32 v17, v0
	v_mov_b32_e32 v18, v0
	v_mov_b32_e32 v19, v0
	v_mov_b32_e32 v20, v0
	v_mov_b32_e32 v21, v0
	v_mov_b32_e32 v22, v0
	v_mov_b32_e32 v23, v0
	v_mov_b32_e32 v32, v0
	v_mov_b32_e32 v33, v0
	v_mov_b32_e32 v34, v0
	v_mov_b32_e32 v35, v0
	v_mov_b32_e32 v36, v0
	v_mov_b32_e32 v37, v0
	v_mov_b32_e32 v38, v0
	v_mov_b32_e32 v39, v0
	v_mov_b32_e32 v48, v0
	v_mov_b32_e32 v49, v0
	v_mov_b32_e32 v50, v0
	v_mov_b32_e32 v51, v0
	v_mov_b32_e32 v52, v0
	v_mov_b32_e32 v53, v0
	v_mov_b32_e32 v54, v0
	v_mov_b32_e32 v55, v0
	v_mov_b32_e32 v8, v0
	v_mov_b32_e32 v9, v0
	v_mov_b32_e32 v10, v0
	v_mov_b32_e32 v11, v0
	v_mov_b32_e32 v12, v0
	v_mov_b32_e32 v13, v0
	v_mov_b32_e32 v14, v0
	v_mov_b32_e32 v15, v0
	v_mov_b32_e32 v24, v0
	v_mov_b32_e32 v25, v0
	v_mov_b32_e32 v26, v0
	v_mov_b32_e32 v27, v0
	v_mov_b32_e32 v28, v0
	v_mov_b32_e32 v29, v0
	v_mov_b32_e32 v30, v0
	v_mov_b32_e32 v31, v0
	v_mov_b32_e32 v40, v0
	v_mov_b32_e32 v41, v0
	v_mov_b32_e32 v42, v0
	v_mov_b32_e32 v43, v0
	v_mov_b32_e32 v44, v0
	v_mov_b32_e32 v45, v0
	v_mov_b32_e32 v46, v0
	v_mov_b32_e32 v47, v0
	v_mov_b32_e32 v56, v0
	v_mov_b32_e32 v57, v0
	v_mov_b32_e32 v58, v0
	v_mov_b32_e32 v59, v0
	v_mov_b32_e32 v60, v0
	v_mov_b32_e32 v61, v0
	v_mov_b32_e32 v62, v0
	v_mov_b32_e32 v63, v0
	v_mov_b32_e32 v64, v0
	v_mov_b32_e32 v65, v0
	v_mov_b32_e32 v66, v0
	v_mov_b32_e32 v67, v0
	v_mov_b32_e32 v68, v0
	v_mov_b32_e32 v69, v0
	v_mov_b32_e32 v70, v0
	v_mov_b32_e32 v71, v0
	v_mov_b32_e32 v80, v0
	v_mov_b32_e32 v81, v0
	v_mov_b32_e32 v82, v0
	v_mov_b32_e32 v83, v0
	v_mov_b32_e32 v84, v0
	v_mov_b32_e32 v85, v0
	v_mov_b32_e32 v86, v0
	v_mov_b32_e32 v87, v0
	v_mov_b32_e32 v96, v0
	v_mov_b32_e32 v97, v0
	v_mov_b32_e32 v98, v0
	v_mov_b32_e32 v99, v0
	v_mov_b32_e32 v100, v0
	v_mov_b32_e32 v101, v0
	v_mov_b32_e32 v102, v0
	v_mov_b32_e32 v103, v0
	v_mov_b32_e32 v112, v0
	v_mov_b32_e32 v113, v0
	v_mov_b32_e32 v114, v0
	v_mov_b32_e32 v115, v0
	v_mov_b32_e32 v116, v0
	v_mov_b32_e32 v117, v0
	v_mov_b32_e32 v118, v0
	v_mov_b32_e32 v119, v0
	v_mov_b32_e32 v72, v0
	v_mov_b32_e32 v73, v0
	v_mov_b32_e32 v74, v0
	v_mov_b32_e32 v75, v0
	v_mov_b32_e32 v76, v0
	v_mov_b32_e32 v77, v0
	v_mov_b32_e32 v78, v0
	v_mov_b32_e32 v79, v0
	v_mov_b32_e32 v88, v0
	v_mov_b32_e32 v89, v0
	v_mov_b32_e32 v90, v0
	v_mov_b32_e32 v91, v0
	v_mov_b32_e32 v92, v0
	v_mov_b32_e32 v93, v0
	v_mov_b32_e32 v94, v0
	v_mov_b32_e32 v95, v0
	v_mov_b32_e32 v104, v0
	v_mov_b32_e32 v105, v0
	v_mov_b32_e32 v106, v0
	v_mov_b32_e32 v107, v0
	v_mov_b32_e32 v108, v0
	v_mov_b32_e32 v109, v0
	v_mov_b32_e32 v110, v0
	v_mov_b32_e32 v111, v0
	v_mov_b32_e32 v120, v0
	v_mov_b32_e32 v121, v0
	v_mov_b32_e32 v122, v0
	v_mov_b32_e32 v123, v0
	v_mov_b32_e32 v124, v0
	v_mov_b32_e32 v125, v0
	v_mov_b32_e32 v126, v0
	v_mov_b32_e32 v127, v0
	.p2alignl 8, 3212836864

.LBB0_1334:
	s_and_b64 vcc, exec, s[10:11]
	s_cbranch_vccnz .LBB0_1332
	.p2alignl 8, 3212836864

.LBB0_1419:
	s_ashr_i32 s27, s26, 31
	s_lshl_b64 s[28:29], s[26:27], 20
	s_add_u32 s28, s48, s28
	s_addc_u32 s29, s49, s29
	s_and_b64 s[30:31], s[8:9], exec
	s_cselect_b32 s27, s29, s39
	s_cselect_b32 s35, s28, s38
	s_ashr_i32 s25, s24, 31
	s_lshl_b64 s[30:31], s[24:25], 20
	s_add_u32 s30, s50, s30
	s_addc_u32 s31, s51, s31
	s_and_b64 s[42:43], s[8:9], exec
	s_cselect_b32 s25, s31, s41
	s_cselect_b32 s65, s30, s40
	s_add_u32 s38, s38, 0x80080
	s_addc_u32 s39, s39, 0
	s_add_u32 s66, s40, 0x100
	v_mov_b32_e32 v0, 0
	s_addc_u32 s67, s41, 0
	s_mov_b32 s68, -2
	s_waitcnt lgkmcnt(0)
	v_mov_b32_e32 v1, v0
	v_mov_b32_e32 v2, v0
	v_mov_b32_e32 v3, v0
	v_mov_b32_e32 v4, v0
	v_mov_b32_e32 v5, v0
	v_mov_b32_e32 v6, v0
	v_mov_b32_e32 v7, v0
	v_mov_b32_e32 v16, v0
	v_mov_b32_e32 v17, v0
	v_mov_b32_e32 v18, v0
	v_mov_b32_e32 v19, v0
	v_mov_b32_e32 v20, v0
	v_mov_b32_e32 v21, v0
	v_mov_b32_e32 v22, v0
	v_mov_b32_e32 v23, v0
	v_mov_b32_e32 v32, v0
	v_mov_b32_e32 v33, v0
	v_mov_b32_e32 v34, v0
	v_mov_b32_e32 v35, v0
	v_mov_b32_e32 v36, v0
	v_mov_b32_e32 v37, v0
	v_mov_b32_e32 v38, v0
	v_mov_b32_e32 v39, v0
	v_mov_b32_e32 v48, v0
	v_mov_b32_e32 v49, v0
	v_mov_b32_e32 v50, v0
	v_mov_b32_e32 v51, v0
	v_mov_b32_e32 v52, v0
	v_mov_b32_e32 v53, v0
	v_mov_b32_e32 v54, v0
	v_mov_b32_e32 v55, v0
	v_mov_b32_e32 v8, v0
	v_mov_b32_e32 v9, v0
	v_mov_b32_e32 v10, v0
	v_mov_b32_e32 v11, v0
	v_mov_b32_e32 v12, v0
	v_mov_b32_e32 v13, v0
	v_mov_b32_e32 v14, v0
	v_mov_b32_e32 v15, v0
	v_mov_b32_e32 v24, v0
	v_mov_b32_e32 v25, v0
	v_mov_b32_e32 v26, v0
	v_mov_b32_e32 v27, v0
	v_mov_b32_e32 v28, v0
	v_mov_b32_e32 v29, v0
	v_mov_b32_e32 v30, v0
	v_mov_b32_e32 v31, v0
	v_mov_b32_e32 v40, v0
	v_mov_b32_e32 v41, v0
	v_mov_b32_e32 v42, v0
	v_mov_b32_e32 v43, v0
	v_mov_b32_e32 v44, v0
	v_mov_b32_e32 v45, v0
	v_mov_b32_e32 v46, v0
	v_mov_b32_e32 v47, v0
	v_mov_b32_e32 v56, v0
	v_mov_b32_e32 v57, v0
	v_mov_b32_e32 v58, v0
	v_mov_b32_e32 v59, v0
	v_mov_b32_e32 v60, v0
	v_mov_b32_e32 v61, v0
	v_mov_b32_e32 v62, v0
	v_mov_b32_e32 v63, v0
	v_mov_b32_e32 v64, v0
	v_mov_b32_e32 v65, v0
	v_mov_b32_e32 v66, v0
	v_mov_b32_e32 v67, v0
	v_mov_b32_e32 v68, v0
	v_mov_b32_e32 v69, v0
	v_mov_b32_e32 v70, v0
	v_mov_b32_e32 v71, v0
	v_mov_b32_e32 v80, v0
	v_mov_b32_e32 v81, v0
	v_mov_b32_e32 v82, v0
	v_mov_b32_e32 v83, v0
	v_mov_b32_e32 v84, v0
	v_mov_b32_e32 v85, v0
	v_mov_b32_e32 v86, v0
	v_mov_b32_e32 v87, v0
	v_mov_b32_e32 v96, v0
	v_mov_b32_e32 v97, v0
	v_mov_b32_e32 v98, v0
	v_mov_b32_e32 v99, v0
	v_mov_b32_e32 v100, v0
	v_mov_b32_e32 v101, v0
	v_mov_b32_e32 v102, v0
	v_mov_b32_e32 v103, v0
	v_mov_b32_e32 v112, v0
	v_mov_b32_e32 v113, v0
	v_mov_b32_e32 v114, v0
	v_mov_b32_e32 v115, v0
	v_mov_b32_e32 v116, v0
	v_mov_b32_e32 v117, v0
	v_mov_b32_e32 v118, v0
	v_mov_b32_e32 v119, v0
	v_mov_b32_e32 v72, v0
	v_mov_b32_e32 v73, v0
	v_mov_b32_e32 v74, v0
	v_mov_b32_e32 v75, v0
	v_mov_b32_e32 v76, v0
	v_mov_b32_e32 v77, v0
	v_mov_b32_e32 v78, v0
	v_mov_b32_e32 v79, v0
	v_mov_b32_e32 v88, v0
	v_mov_b32_e32 v89, v0
	v_mov_b32_e32 v90, v0
	v_mov_b32_e32 v91, v0
	v_mov_b32_e32 v92, v0
	v_mov_b32_e32 v93, v0
	v_mov_b32_e32 v94, v0
	v_mov_b32_e32 v95, v0
	v_mov_b32_e32 v104, v0
	v_mov_b32_e32 v105, v0
	v_mov_b32_e32 v106, v0
	v_mov_b32_e32 v107, v0
	v_mov_b32_e32 v108, v0
	v_mov_b32_e32 v109, v0
	v_mov_b32_e32 v110, v0
	v_mov_b32_e32 v111, v0
	v_mov_b32_e32 v120, v0
	v_mov_b32_e32 v121, v0
	v_mov_b32_e32 v122, v0
	v_mov_b32_e32 v123, v0
	v_mov_b32_e32 v124, v0
	v_mov_b32_e32 v125, v0
	v_mov_b32_e32 v126, v0
	v_mov_b32_e32 v127, v0
	.p2alignl 8, 3212836864

.LBB0_1503:
	s_ashr_i32 s23, s22, 31
	s_lshl_b64 s[24:25], s[22:23], 20
	s_add_u32 s24, s36, s24
	s_addc_u32 s25, s37, s25
	s_and_b64 s[26:27], s[6:7], exec
	s_cselect_b32 s23, s25, s29
	s_cselect_b32 s61, s24, s28
	s_ashr_i32 s21, s20, 31
	s_lshl_b64 s[26:27], s[20:21], 20
	s_add_u32 s26, s38, s26
	s_addc_u32 s27, s39, s27
	s_and_b64 s[34:35], s[6:7], exec
	s_cselect_b32 s21, s27, s31
	s_cselect_b32 s62, s26, s30
	s_add_u32 s28, s28, 0x80080
	s_addc_u32 s29, s29, 0
	s_add_u32 s63, s30, 0x100
	v_mov_b32_e32 v8, 0
	s_addc_u32 s64, s31, 0
	s_mov_b32 s65, -2
	v_mov_b32_e32 v9, v8
	v_mov_b32_e32 v10, v8
	v_mov_b32_e32 v11, v8
	v_mov_b32_e32 v12, v8
	v_mov_b32_e32 v13, v8
	v_mov_b32_e32 v14, v8
	v_mov_b32_e32 v15, v8
	v_mov_b32_e32 v24, v8
	v_mov_b32_e32 v25, v8
	v_mov_b32_e32 v26, v8
	v_mov_b32_e32 v27, v8
	v_mov_b32_e32 v28, v8
	v_mov_b32_e32 v29, v8
	v_mov_b32_e32 v30, v8
	v_mov_b32_e32 v31, v8
	v_mov_b32_e32 v40, v8
	v_mov_b32_e32 v41, v8
	v_mov_b32_e32 v42, v8
	v_mov_b32_e32 v43, v8
	v_mov_b32_e32 v44, v8
	v_mov_b32_e32 v45, v8
	v_mov_b32_e32 v46, v8
	v_mov_b32_e32 v47, v8
	v_mov_b32_e32 v56, v8
	v_mov_b32_e32 v57, v8
	v_mov_b32_e32 v58, v8
	v_mov_b32_e32 v59, v8
	v_mov_b32_e32 v60, v8
	v_mov_b32_e32 v61, v8
	v_mov_b32_e32 v62, v8
	v_mov_b32_e32 v63, v8
	v_mov_b32_e32 v0, v8
	v_mov_b32_e32 v1, v8
	v_mov_b32_e32 v2, v8
	v_mov_b32_e32 v3, v8
	v_mov_b32_e32 v4, v8
	v_mov_b32_e32 v5, v8
	v_mov_b32_e32 v6, v8
	v_mov_b32_e32 v7, v8
	v_mov_b32_e32 v16, v8
	v_mov_b32_e32 v17, v8
	v_mov_b32_e32 v18, v8
	v_mov_b32_e32 v19, v8
	v_mov_b32_e32 v20, v8
	v_mov_b32_e32 v21, v8
	v_mov_b32_e32 v22, v8
	v_mov_b32_e32 v23, v8
	v_mov_b32_e32 v32, v8
	v_mov_b32_e32 v33, v8
	v_mov_b32_e32 v34, v8
	v_mov_b32_e32 v35, v8
	v_mov_b32_e32 v36, v8
	v_mov_b32_e32 v37, v8
	v_mov_b32_e32 v38, v8
	v_mov_b32_e32 v39, v8
	v_mov_b32_e32 v48, v8
	v_mov_b32_e32 v49, v8
	v_mov_b32_e32 v50, v8
	v_mov_b32_e32 v51, v8
	v_mov_b32_e32 v52, v8
	v_mov_b32_e32 v53, v8
	v_mov_b32_e32 v54, v8
	v_mov_b32_e32 v55, v8
	v_mov_b32_e32 v72, v8
	v_mov_b32_e32 v73, v8
	v_mov_b32_e32 v74, v8
	v_mov_b32_e32 v75, v8
	v_mov_b32_e32 v76, v8
	v_mov_b32_e32 v77, v8
	v_mov_b32_e32 v78, v8
	v_mov_b32_e32 v79, v8
	v_mov_b32_e32 v88, v8
	v_mov_b32_e32 v89, v8
	v_mov_b32_e32 v90, v8
	v_mov_b32_e32 v91, v8
	v_mov_b32_e32 v92, v8
	v_mov_b32_e32 v93, v8
	v_mov_b32_e32 v94, v8
	v_mov_b32_e32 v95, v8
	v_mov_b32_e32 v104, v8
	v_mov_b32_e32 v105, v8
	v_mov_b32_e32 v106, v8
	v_mov_b32_e32 v107, v8
	v_mov_b32_e32 v108, v8
	v_mov_b32_e32 v109, v8
	v_mov_b32_e32 v110, v8
	v_mov_b32_e32 v111, v8
	v_mov_b32_e32 v120, v8
	v_mov_b32_e32 v121, v8
	v_mov_b32_e32 v122, v8
	v_mov_b32_e32 v123, v8
	v_mov_b32_e32 v124, v8
	v_mov_b32_e32 v125, v8
	v_mov_b32_e32 v126, v8
	v_mov_b32_e32 v127, v8
	v_mov_b32_e32 v64, v8
	v_mov_b32_e32 v65, v8
	v_mov_b32_e32 v66, v8
	v_mov_b32_e32 v67, v8
	v_mov_b32_e32 v68, v8
	v_mov_b32_e32 v69, v8
	v_mov_b32_e32 v70, v8
	v_mov_b32_e32 v71, v8
	v_mov_b32_e32 v80, v8
	v_mov_b32_e32 v81, v8
	v_mov_b32_e32 v82, v8
	v_mov_b32_e32 v83, v8
	v_mov_b32_e32 v84, v8
	v_mov_b32_e32 v85, v8
	v_mov_b32_e32 v86, v8
	v_mov_b32_e32 v87, v8
	v_mov_b32_e32 v96, v8
	v_mov_b32_e32 v97, v8
	v_mov_b32_e32 v98, v8
	v_mov_b32_e32 v99, v8
	v_mov_b32_e32 v100, v8
	v_mov_b32_e32 v101, v8
	v_mov_b32_e32 v102, v8
	v_mov_b32_e32 v103, v8
	v_mov_b32_e32 v112, v8
	v_mov_b32_e32 v113, v8
	v_mov_b32_e32 v114, v8
	v_mov_b32_e32 v115, v8
	v_mov_b32_e32 v116, v8
	v_mov_b32_e32 v117, v8
	v_mov_b32_e32 v118, v8
	v_mov_b32_e32 v119, v8
	.p2alignl 8, 3212836864

.LBB0_2112:
	s_add_u32 s21, s26, 0x100
	s_addc_u32 s53, s27, 0
	v_lshl_add_u64 v[144:145], s[24:25], 0, v[136:137]
	v_lshl_add_u64 v[146:147], s[24:25], 0, v[138:139]
	s_mov_b32 s54, -2
	s_mov_b64 s[26:27], 0
	.p2alignl 8, 3212836864
